# odd_prep MLA rows: all loads of both rows issued together before the row loop
# speedup vs baseline: 1.0087x; 1.0087x over previous
.LBB0_553:
	s_waitcnt vmcnt(0)
	v_lshlrev_b32_e32 v72, 16, v72
	v_lshlrev_b32_e32 v46, 16, v46
	v_lshlrev_b32_e32 v83, 16, v83
	v_lshlrev_b32_e32 v50, 16, v50
	v_lshlrev_b32_e32 v89, 16, v89
	v_lshlrev_b32_e32 v7, 16, v7
	v_lshlrev_b32_e32 v27, 16, v86
	v_lshlrev_b32_e32 v29, 16, v91
	v_mul_f32_e32 v22, v47, v27
	v_mul_f32_e32 v23, v55, v29
	v_fmac_f32_e32 v22, v43, v83
	v_lshlrev_b32_e32 v28, 16, v85
	v_fmac_f32_e32 v23, v54, v89
	v_lshlrev_b32_e32 v30, 16, v90
	v_lshlrev_b32_e32 v5, 16, v80
	v_fmac_f32_e32 v22, v49, v28
	v_fmac_f32_e32 v23, v6, v30
	v_mul_f32_e32 v21, v45, v5
	v_add_f32_e32 v22, v42, v22
	v_add_f32_e32 v23, v8, v23
	v_fmac_f32_e32 v21, v9, v72
	v_lshlrev_b32_e32 v26, 16, v79
	v_mul_f32_e32 v22, v22, v23
	v_fmac_f32_e32 v21, v44, v26
	v_bfe_u32 v23, v22, 16, 1
	v_add_f32_e32 v21, v0, v21
	v_add3_u32 v22, v22, v23, s27
	v_lshrrev_b32_e32 v31, 16, v22
	v_bfe_u32 v22, v21, 16, 1
	s_lshl_b64 s[4:5], s[44:45], 9
	v_add3_u32 v21, v21, v22, s27
	v_lshl_add_u64 v[22:23], s[4:5], 0, v[2:3]
	v_readlane_b32 s10, v254, 49
	v_lshlrev_b64 v[22:23], 1, v[22:23]
	v_readlane_b32 s11, v254, 50
	v_lshl_add_u32 v4, v2, 1, 0
	ds_write_b16 v4, v31
	v_lshl_add_u64 v[24:25], s[10:11], 0, v[22:23]
	v_lshl_add_u64 v[22:23], s[0:1], 0, v[22:23]
	global_store_short v[22:23], v31, off
	v_mul_f32_e32 v22, v47, v28
	v_mul_f32_e32 v23, v55, v30
	v_fmac_f32_e32 v22, v43, v27
	v_lshlrev_b32_e32 v27, 16, v82
	v_fmac_f32_e32 v23, v54, v29
	v_lshlrev_b32_e32 v29, 16, v88
	v_fmac_f32_e32 v22, v49, v27
	v_fmac_f32_e32 v23, v6, v29
	global_store_short_d16_hi v[24:25], v21, off
	v_mul_f32_e32 v21, v45, v26
	v_add_f32_e32 v22, v42, v22
	v_add_f32_e32 v23, v8, v23
	v_fmac_f32_e32 v21, v9, v5
	v_lshlrev_b32_e32 v5, 16, v77
	v_mul_f32_e32 v22, v22, v23
	v_fmac_f32_e32 v21, v44, v5
	v_bfe_u32 v23, v22, 16, 1
	v_add_f32_e32 v21, v0, v21
	v_add3_u32 v22, v22, v23, s27
	v_lshrrev_b32_e32 v31, 16, v22
	v_bfe_u32 v22, v21, 16, 1
	s_lshl_b64 s[4:5], s[76:77], 9
	v_add3_u32 v21, v21, v22, s27
	v_lshl_add_u64 v[22:23], s[4:5], 0, v[2:3]
	v_lshlrev_b64 v[22:23], 1, v[22:23]
	v_lshl_add_u64 v[24:25], s[10:11], 0, v[22:23]
	v_lshl_add_u64 v[22:23], s[0:1], 0, v[22:23]
	global_store_short v[22:23], v31, off
	v_mul_f32_e32 v22, v47, v27
	v_mul_f32_e32 v23, v55, v29
	v_fmac_f32_e32 v22, v43, v28
	v_lshlrev_b32_e32 v28, 16, v81
	v_fmac_f32_e32 v23, v54, v30
	v_lshlrev_b32_e32 v30, 16, v87
	v_fmac_f32_e32 v22, v49, v28
	v_fmac_f32_e32 v23, v6, v30
	global_store_short_d16_hi v[24:25], v21, off
	v_mul_f32_e32 v21, v45, v5
	v_add_f32_e32 v22, v42, v22
	v_add_f32_e32 v23, v8, v23
	v_fmac_f32_e32 v21, v9, v26
	v_lshlrev_b32_e32 v26, 16, v75
	v_mul_f32_e32 v22, v22, v23
	v_fmac_f32_e32 v21, v44, v26
	v_bfe_u32 v23, v22, 16, 1
	v_add_f32_e32 v21, v0, v21
	v_add3_u32 v22, v22, v23, s27
	ds_write_b16 v4, v31 offset:1040
	v_lshrrev_b32_e32 v31, 16, v22
	v_bfe_u32 v22, v21, 16, 1
	s_lshl_b64 s[4:5], s[74:75], 9
	v_add3_u32 v21, v21, v22, s27
	v_lshl_add_u64 v[22:23], s[4:5], 0, v[2:3]
	v_lshlrev_b64 v[22:23], 1, v[22:23]
	v_lshl_add_u64 v[24:25], s[10:11], 0, v[22:23]
	v_lshl_add_u64 v[22:23], s[0:1], 0, v[22:23]
	global_store_short v[22:23], v31, off
	v_mul_f32_e32 v22, v47, v28
	v_mul_f32_e32 v23, v55, v30
	v_fmac_f32_e32 v22, v43, v27
	v_lshlrev_b32_e32 v27, 16, v78
	v_fmac_f32_e32 v23, v54, v29
	v_lshlrev_b32_e32 v29, 16, v84
	v_fmac_f32_e32 v22, v49, v27
	v_fmac_f32_e32 v23, v6, v29
	global_store_short_d16_hi v[24:25], v21, off
	v_mul_f32_e32 v21, v45, v26
	v_add_f32_e32 v22, v42, v22
	v_add_f32_e32 v23, v8, v23
	v_fmac_f32_e32 v21, v9, v5
	v_lshlrev_b32_e32 v5, 16, v73
	v_mul_f32_e32 v22, v22, v23
	v_fmac_f32_e32 v21, v44, v5
	v_bfe_u32 v23, v22, 16, 1
	v_add_f32_e32 v21, v0, v21
	v_add3_u32 v22, v22, v23, s27
	ds_write_b16 v4, v31 offset:2080
	v_lshrrev_b32_e32 v31, 16, v22
	v_bfe_u32 v22, v21, 16, 1
	s_lshl_b64 s[4:5], s[72:73], 9
	v_add3_u32 v21, v21, v22, s27
	v_lshl_add_u64 v[22:23], s[4:5], 0, v[2:3]
	v_lshlrev_b64 v[22:23], 1, v[22:23]
	v_lshl_add_u64 v[24:25], s[10:11], 0, v[22:23]
	v_lshl_add_u64 v[22:23], s[0:1], 0, v[22:23]
	global_store_short_d16_hi v[24:25], v21, off
	global_store_short v[22:23], v31, off
	v_mul_f32_e32 v21, v45, v5
	v_mul_f32_e32 v22, v47, v27
	v_mul_f32_e32 v23, v55, v29
	v_fmac_f32_e32 v21, v9, v26
	v_fmac_f32_e32 v22, v43, v28
	v_lshlrev_b32_e32 v25, 16, v76
	v_fmac_f32_e32 v23, v54, v30
	v_lshlrev_b32_e32 v26, 16, v20
	v_fmac_f32_e32 v22, v49, v25
	v_fmac_f32_e32 v23, v6, v26
	v_add_f32_e32 v22, v42, v22
	v_add_f32_e32 v20, v8, v23
	v_lshlrev_b32_e32 v24, 16, v70
	v_mul_f32_e32 v20, v22, v20
	v_fmac_f32_e32 v21, v44, v24
	v_bfe_u32 v22, v20, 16, 1
	v_add_f32_e32 v21, v0, v21
	v_add3_u32 v20, v20, v22, s27
	v_lshrrev_b32_e32 v28, 16, v20
	v_bfe_u32 v20, v21, 16, 1
	s_lshl_b64 s[4:5], s[70:71], 9
	v_add3_u32 v30, v21, v20, s27
	v_lshl_add_u64 v[20:21], s[4:5], 0, v[2:3]
	v_lshlrev_b64 v[20:21], 1, v[20:21]
	v_lshl_add_u64 v[22:23], s[10:11], 0, v[20:21]
	v_lshl_add_u64 v[20:21], s[0:1], 0, v[20:21]
	global_store_short_d16_hi v[22:23], v30, off
	global_store_short v[20:21], v28, off
	v_mul_f32_e32 v21, v47, v25
	v_mul_f32_e32 v22, v55, v26
	ds_write_b16 v4, v28 offset:4160
	v_fmac_f32_e32 v21, v43, v27
	v_lshlrev_b32_e32 v27, 16, v74
	v_fmac_f32_e32 v22, v54, v29
	v_lshlrev_b32_e32 v28, 16, v19
	v_mul_f32_e32 v20, v45, v24
	v_fmac_f32_e32 v21, v49, v27
	v_fmac_f32_e32 v22, v6, v28
	v_fmac_f32_e32 v20, v9, v5
	v_lshlrev_b32_e32 v5, 16, v68
	v_add_f32_e32 v21, v42, v21
	v_add_f32_e32 v19, v8, v22
	v_fmac_f32_e32 v20, v44, v5
	v_mul_f32_e32 v19, v21, v19
	v_add_f32_e32 v20, v0, v20
	v_bfe_u32 v21, v19, 16, 1
	v_add3_u32 v19, v19, v21, s27
	v_bfe_u32 v21, v20, 16, 1
	s_lshl_b64 s[4:5], s[68:69], 9
	v_add3_u32 v29, v20, v21, s27
	v_lshl_add_u64 v[20:21], s[4:5], 0, v[2:3]
	v_lshlrev_b64 v[20:21], 1, v[20:21]
	v_lshrrev_b32_e32 v19, 16, v19
	v_lshl_add_u64 v[22:23], s[10:11], 0, v[20:21]
	v_lshl_add_u64 v[20:21], s[0:1], 0, v[20:21]
	global_store_short v[20:21], v19, off
	ds_write_b16 v4, v19 offset:5200
	v_mul_f32_e32 v19, v45, v5
	v_mul_f32_e32 v20, v47, v27
	v_mul_f32_e32 v21, v55, v28
	global_store_short_d16_hi v[22:23], v29, off
	v_fmac_f32_e32 v19, v9, v24
	v_fmac_f32_e32 v20, v43, v25
	v_lshlrev_b32_e32 v23, 16, v71
	v_fmac_f32_e32 v21, v54, v26
	v_lshlrev_b32_e32 v24, 16, v18
	v_fmac_f32_e32 v20, v49, v23
	v_fmac_f32_e32 v21, v6, v24
	v_add_f32_e32 v20, v42, v20
	v_add_f32_e32 v18, v8, v21
	v_lshlrev_b32_e32 v22, 16, v66
	v_mul_f32_e32 v18, v20, v18
	v_fmac_f32_e32 v19, v44, v22
	v_bfe_u32 v20, v18, 16, 1
	v_add_f32_e32 v19, v0, v19
	v_add3_u32 v18, v18, v20, s27
	v_lshrrev_b32_e32 v25, 16, v18
	v_bfe_u32 v18, v19, 16, 1
	s_lshl_b64 s[4:5], s[66:67], 9
	v_add3_u32 v26, v19, v18, s27
	v_lshl_add_u64 v[18:19], s[4:5], 0, v[2:3]
	v_lshlrev_b64 v[18:19], 1, v[18:19]
	v_lshl_add_u64 v[20:21], s[10:11], 0, v[18:19]
	v_lshl_add_u64 v[18:19], s[0:1], 0, v[18:19]
	global_store_short_d16_hi v[20:21], v26, off
	global_store_short v[18:19], v25, off
	v_mul_f32_e32 v19, v47, v23
	v_mul_f32_e32 v20, v55, v24
	ds_write_b16 v4, v25 offset:6240
	v_fmac_f32_e32 v19, v43, v27
	v_lshlrev_b32_e32 v25, 16, v69
	v_fmac_f32_e32 v20, v54, v28
	v_lshlrev_b32_e32 v26, 16, v17
	v_mul_f32_e32 v18, v45, v22
	v_fmac_f32_e32 v19, v49, v25
	v_fmac_f32_e32 v20, v6, v26
	v_fmac_f32_e32 v18, v9, v5
	v_lshlrev_b32_e32 v5, 16, v64
	v_add_f32_e32 v19, v42, v19
	v_add_f32_e32 v17, v8, v20
	v_fmac_f32_e32 v18, v44, v5
	v_mul_f32_e32 v17, v19, v17
	v_add_f32_e32 v18, v0, v18
	v_bfe_u32 v19, v17, 16, 1
	v_add3_u32 v17, v17, v19, s27
	v_bfe_u32 v19, v18, 16, 1
	s_lshl_b64 s[4:5], s[64:65], 9
	v_add3_u32 v27, v18, v19, s27
	v_lshl_add_u64 v[18:19], s[4:5], 0, v[2:3]
	v_lshlrev_b64 v[18:19], 1, v[18:19]
	v_lshrrev_b32_e32 v17, 16, v17
	v_lshl_add_u64 v[20:21], s[10:11], 0, v[18:19]
	v_lshl_add_u64 v[18:19], s[0:1], 0, v[18:19]
	global_store_short v[18:19], v17, off
	ds_write_b16 v4, v17 offset:7280
	v_mul_f32_e32 v17, v45, v5
	v_mul_f32_e32 v18, v47, v25
	v_mul_f32_e32 v19, v55, v26
	global_store_short_d16_hi v[20:21], v27, off
	v_fmac_f32_e32 v17, v9, v22
	v_fmac_f32_e32 v18, v43, v23
	v_lshlrev_b32_e32 v21, 16, v67
	v_fmac_f32_e32 v19, v54, v24
	v_lshlrev_b32_e32 v22, 16, v16
	v_fmac_f32_e32 v18, v49, v21
	v_fmac_f32_e32 v19, v6, v22
	v_add_f32_e32 v18, v42, v18
	v_add_f32_e32 v16, v8, v19
	v_lshlrev_b32_e32 v20, 16, v62
	v_mul_f32_e32 v16, v18, v16
	v_fmac_f32_e32 v17, v44, v20
	v_bfe_u32 v18, v16, 16, 1
	v_add_f32_e32 v17, v0, v17
	v_add3_u32 v16, v16, v18, s27
	v_lshrrev_b32_e32 v23, 16, v16
	v_bfe_u32 v16, v17, 16, 1
	s_lshl_b64 s[4:5], s[62:63], 9
	v_add3_u32 v24, v17, v16, s27
	v_lshl_add_u64 v[16:17], s[4:5], 0, v[2:3]
	v_lshlrev_b64 v[16:17], 1, v[16:17]
	v_lshl_add_u64 v[18:19], s[10:11], 0, v[16:17]
	v_lshl_add_u64 v[16:17], s[0:1], 0, v[16:17]
	global_store_short_d16_hi v[18:19], v24, off
	global_store_short v[16:17], v23, off
	v_mul_f32_e32 v17, v47, v21
	v_mul_f32_e32 v18, v55, v22
	ds_write_b16 v4, v23 offset:8320
	v_fmac_f32_e32 v17, v43, v25
	v_lshlrev_b32_e32 v23, 16, v65
	v_fmac_f32_e32 v18, v54, v26
	v_lshlrev_b32_e32 v24, 16, v15
	v_mul_f32_e32 v16, v45, v20
	v_fmac_f32_e32 v17, v49, v23
	v_fmac_f32_e32 v18, v6, v24
	v_fmac_f32_e32 v16, v9, v5
	v_lshlrev_b32_e32 v5, 16, v60
	v_add_f32_e32 v17, v42, v17
	v_add_f32_e32 v15, v8, v18
	v_fmac_f32_e32 v16, v44, v5
	v_mul_f32_e32 v15, v17, v15
	v_add_f32_e32 v16, v0, v16
	v_bfe_u32 v17, v15, 16, 1
	v_add3_u32 v15, v15, v17, s27
	v_bfe_u32 v17, v16, 16, 1
	s_lshl_b64 s[4:5], s[60:61], 9
	v_add3_u32 v25, v16, v17, s27
	v_lshl_add_u64 v[16:17], s[4:5], 0, v[2:3]
	v_lshlrev_b64 v[16:17], 1, v[16:17]
	v_lshrrev_b32_e32 v15, 16, v15
	v_lshl_add_u64 v[18:19], s[10:11], 0, v[16:17]
	v_lshl_add_u64 v[16:17], s[0:1], 0, v[16:17]
	global_store_short v[16:17], v15, off
	ds_write_b16 v4, v15 offset:9360
	v_mul_f32_e32 v15, v45, v5
	v_mul_f32_e32 v16, v47, v23
	v_mul_f32_e32 v17, v55, v24
	global_store_short_d16_hi v[18:19], v25, off
	v_fmac_f32_e32 v15, v9, v20
	v_fmac_f32_e32 v16, v43, v21
	v_lshlrev_b32_e32 v19, 16, v63
	v_fmac_f32_e32 v17, v54, v22
	v_lshlrev_b32_e32 v20, 16, v14
	v_fmac_f32_e32 v16, v49, v19
	v_fmac_f32_e32 v17, v6, v20
	v_add_f32_e32 v16, v42, v16
	v_add_f32_e32 v14, v8, v17
	v_lshlrev_b32_e32 v18, 16, v58
	v_mul_f32_e32 v14, v16, v14
	v_fmac_f32_e32 v15, v44, v18
	v_bfe_u32 v16, v14, 16, 1
	v_add_f32_e32 v15, v0, v15
	v_add3_u32 v14, v14, v16, s27
	v_lshrrev_b32_e32 v21, 16, v14
	v_bfe_u32 v14, v15, 16, 1
	s_lshl_b64 s[4:5], s[58:59], 9
	v_add3_u32 v22, v15, v14, s27
	v_lshl_add_u64 v[14:15], s[4:5], 0, v[2:3]
	v_lshlrev_b64 v[14:15], 1, v[14:15]
	v_lshl_add_u64 v[16:17], s[10:11], 0, v[14:15]
	v_lshl_add_u64 v[14:15], s[0:1], 0, v[14:15]
	global_store_short_d16_hi v[16:17], v22, off
	global_store_short v[14:15], v21, off
	v_mul_f32_e32 v15, v47, v19
	v_mul_f32_e32 v16, v55, v20
	ds_write_b16 v4, v21 offset:10400
	v_fmac_f32_e32 v15, v43, v23
	v_lshlrev_b32_e32 v21, 16, v61
	v_fmac_f32_e32 v16, v54, v24
	v_lshlrev_b32_e32 v22, 16, v13
	v_mul_f32_e32 v14, v45, v18
	v_fmac_f32_e32 v15, v49, v21
	v_fmac_f32_e32 v16, v6, v22
	v_fmac_f32_e32 v14, v9, v5
	v_lshlrev_b32_e32 v5, 16, v56
	v_add_f32_e32 v15, v42, v15
	v_add_f32_e32 v13, v8, v16
	v_fmac_f32_e32 v14, v44, v5
	v_mul_f32_e32 v13, v15, v13
	v_add_f32_e32 v14, v0, v14
	v_bfe_u32 v15, v13, 16, 1
	v_add3_u32 v13, v13, v15, s27
	v_bfe_u32 v15, v14, 16, 1
	s_lshl_b64 s[4:5], s[56:57], 9
	v_add3_u32 v23, v14, v15, s27
	v_lshl_add_u64 v[14:15], s[4:5], 0, v[2:3]
	v_lshlrev_b64 v[14:15], 1, v[14:15]
	v_lshrrev_b32_e32 v13, 16, v13
	v_lshl_add_u64 v[16:17], s[10:11], 0, v[14:15]
	v_lshl_add_u64 v[14:15], s[0:1], 0, v[14:15]
	global_store_short v[14:15], v13, off
	ds_write_b16 v4, v13 offset:11440
	v_mul_f32_e32 v13, v45, v5
	v_mul_f32_e32 v14, v47, v21
	v_mul_f32_e32 v15, v55, v22
	global_store_short_d16_hi v[16:17], v23, off
	v_fmac_f32_e32 v13, v9, v18
	v_fmac_f32_e32 v14, v43, v19
	v_lshlrev_b32_e32 v17, 16, v59
	v_fmac_f32_e32 v15, v54, v20
	v_lshlrev_b32_e32 v18, 16, v12
	v_fmac_f32_e32 v14, v49, v17
	v_fmac_f32_e32 v15, v6, v18
	v_add_f32_e32 v14, v42, v14
	v_add_f32_e32 v12, v8, v15
	v_lshlrev_b32_e32 v16, 16, v52
	v_mul_f32_e32 v12, v14, v12
	v_fmac_f32_e32 v13, v44, v16
	v_bfe_u32 v14, v12, 16, 1
	v_add_f32_e32 v13, v0, v13
	v_add3_u32 v12, v12, v14, s27
	v_lshrrev_b32_e32 v19, 16, v12
	v_bfe_u32 v12, v13, 16, 1
	s_lshl_b64 s[4:5], s[54:55], 9
	v_add3_u32 v20, v13, v12, s27
	v_lshl_add_u64 v[12:13], s[4:5], 0, v[2:3]
	v_lshlrev_b64 v[12:13], 1, v[12:13]
	v_lshl_add_u64 v[14:15], s[10:11], 0, v[12:13]
	v_lshl_add_u64 v[12:13], s[0:1], 0, v[12:13]
	global_store_short_d16_hi v[14:15], v20, off
	global_store_short v[12:13], v19, off
	v_mul_f32_e32 v13, v47, v17
	v_mul_f32_e32 v14, v55, v18
	ds_write_b16 v4, v19 offset:12480
	v_fmac_f32_e32 v13, v43, v21
	v_lshlrev_b32_e32 v19, 16, v57
	v_fmac_f32_e32 v14, v54, v22
	v_lshlrev_b32_e32 v20, 16, v11
	v_mul_f32_e32 v12, v45, v16
	v_fmac_f32_e32 v13, v49, v19
	v_fmac_f32_e32 v14, v6, v20
	v_fmac_f32_e32 v12, v9, v5
	v_lshlrev_b32_e32 v5, 16, v51
	v_add_f32_e32 v13, v42, v13
	v_add_f32_e32 v11, v8, v14
	v_fmac_f32_e32 v12, v44, v5
	v_mul_f32_e32 v11, v13, v11
	v_add_f32_e32 v12, v0, v12
	v_bfe_u32 v13, v11, 16, 1
	v_add3_u32 v11, v11, v13, s27
	v_bfe_u32 v13, v12, 16, 1
	s_lshl_b64 s[4:5], s[52:53], 9
	v_add3_u32 v21, v12, v13, s27
	v_lshl_add_u64 v[12:13], s[4:5], 0, v[2:3]
	v_lshlrev_b64 v[12:13], 1, v[12:13]
	v_lshrrev_b32_e32 v11, 16, v11
	v_lshl_add_u64 v[14:15], s[10:11], 0, v[12:13]
	v_lshl_add_u64 v[12:13], s[0:1], 0, v[12:13]
	global_store_short v[12:13], v11, off
	ds_write_b16 v4, v11 offset:13520
	v_mul_f32_e32 v11, v45, v5
	v_mul_f32_e32 v12, v47, v19
	v_mul_f32_e32 v13, v55, v20
	global_store_short_d16_hi v[14:15], v21, off
	v_fmac_f32_e32 v11, v9, v16
	v_fmac_f32_e32 v12, v43, v17
	v_lshlrev_b32_e32 v15, 16, v53
	v_fmac_f32_e32 v13, v54, v18
	v_lshlrev_b32_e32 v16, 16, v10
	v_fmac_f32_e32 v12, v49, v15
	v_fmac_f32_e32 v13, v6, v16
	v_add_f32_e32 v12, v42, v12
	v_add_f32_e32 v10, v8, v13
	v_lshlrev_b32_e32 v14, 16, v48
	v_mul_f32_e32 v10, v12, v10
	v_fmac_f32_e32 v11, v44, v14
	v_bfe_u32 v12, v10, 16, 1
	v_add_f32_e32 v11, v0, v11
	v_add3_u32 v10, v10, v12, s27
	v_lshrrev_b32_e32 v17, 16, v10
	v_bfe_u32 v10, v11, 16, 1
	s_lshl_b64 s[4:5], s[50:51], 9
	v_add3_u32 v18, v11, v10, s27
	v_lshl_add_u64 v[10:11], s[4:5], 0, v[2:3]
	v_lshlrev_b64 v[10:11], 1, v[10:11]
	v_lshl_add_u64 v[12:13], s[10:11], 0, v[10:11]
	v_lshl_add_u64 v[10:11], s[0:1], 0, v[10:11]
	global_store_short v[10:11], v17, off
	v_mul_f32_e32 v10, v45, v14
	v_fmac_f32_e32 v10, v9, v5
	v_mul_f32_e32 v5, v47, v15
	v_mul_f32_e32 v9, v55, v16
	v_fmac_f32_e32 v5, v43, v19
	v_fmac_f32_e32 v9, v54, v20
	v_fmac_f32_e32 v5, v49, v50
	v_fmac_f32_e32 v9, v6, v7
	v_add_f32_e32 v5, v42, v5
	v_add_f32_e32 v6, v8, v9
	v_fmac_f32_e32 v10, v44, v46
	v_mul_f32_e32 v5, v5, v6
	v_add_f32_e32 v0, v0, v10
	v_bfe_u32 v6, v5, 16, 1
	v_add3_u32 v5, v5, v6, s27
	v_bfe_u32 v6, v0, 16, 1
	s_lshl_b64 s[4:5], s[48:49], 9
	v_add3_u32 v0, v0, v6, s27
	v_lshl_add_u64 v[6:7], s[4:5], 0, v[2:3]
	v_lshlrev_b64 v[6:7], 1, v[6:7]
	v_lshrrev_b32_e32 v5, 16, v5
	v_lshl_add_u64 v[8:9], s[10:11], 0, v[6:7]
	v_lshl_add_u64 v[6:7], s[0:1], 0, v[6:7]
	ds_write_b16 v4, v31 offset:3120
	global_store_short_d16_hi v[12:13], v18, off
	ds_write_b16 v4, v17 offset:14560
	global_store_short_d16_hi v[8:9], v0, off
	global_store_short v[6:7], v5, off
	ds_write_b16 v4, v5 offset:15600
	s_waitcnt lgkmcnt(0)
	s_barrier
	ds_read_u16 v0, v4
	ds_read_u16 v3, v4 offset:1040
	ds_read_u16 v5, v4 offset:2080
	ds_read_u16 v8, v4 offset:3120
	ds_read_u16 v9, v4 offset:4160
	ds_read_u16 v12, v4 offset:5200
	ds_read_u16 v13, v4 offset:6240
	ds_read_u16 v14, v4 offset:7280
	v_readlane_b32 s4, v254, 47
	v_readlane_b32 s5, v254, 48
	s_movk_i32 s68, 0x3000
	v_ashrrev_i32_e32 v24, 6, v2
	v_mov_b64_e32 v[6:7], s[4:5]
	v_mad_i64_i32 v[6:7], s[4:5], v2, s68, v[6:7]
	v_lshl_add_u64 v[10:11], s[44:45], 1, v[6:7]
	s_waitcnt lgkmcnt(6)
	v_lshl_or_b32 v6, v3, 16, v0
	s_waitcnt lgkmcnt(4)
	v_lshl_or_b32 v7, v8, 16, v5
	s_waitcnt lgkmcnt(2)
	v_lshl_or_b32 v8, v12, 16, v9
	s_waitcnt lgkmcnt(0)
	v_lshl_or_b32 v9, v14, 16, v13
	ds_read_u16 v0, v4 offset:8320
	ds_read_u16 v3, v4 offset:9360
	ds_read_u16 v5, v4 offset:10400
	ds_read_u16 v12, v4 offset:11440
	ds_read_u16 v13, v4 offset:12480
	ds_read_u16 v14, v4 offset:13520
	ds_read_u16 v15, v4 offset:14560
	ds_read_u16 v16, v4 offset:15600
	global_store_dwordx4 v[10:11], v[6:9], off
	s_waitcnt lgkmcnt(6)
	v_lshl_or_b32 v4, v3, 16, v0
	s_waitcnt lgkmcnt(4)
	v_lshl_or_b32 v5, v12, 16, v5
	s_waitcnt lgkmcnt(2)
	v_lshl_or_b32 v6, v14, 16, v13
	s_waitcnt lgkmcnt(0)
	v_lshl_or_b32 v7, v16, 16, v15
	v_cmp_gt_i32_e32 vcc, 16, v24
	global_store_dwordx4 v[10:11], v[4:7], off offset:16
	s_and_saveexec_b64 s[46:47], vcc
	v_readlane_b32 s70, v254, 34
	v_readlane_b32 s58, v254, 44
	v_readlane_b32 s56, v254, 32
	s_mov_b32 s57, 0xe0000
	v_readlane_b32 s69, v253, 27
	s_mov_b64 s[16:17], 0x1000
	s_mov_b64 s[18:19], 0x8000
	v_readlane_b32 s71, v254, 35
	v_readlane_b32 s72, v254, 36
	v_readlane_b32 s59, v254, 45
	s_cbranch_execz .LBB0_540
	v_and_b32_e32 v3, 64, v210
	v_add_u32_e32 v3, 64, v3
	v_xor_b32_e32 v4, 32, v210
	v_cmp_lt_i32_e32 vcc, v4, v3
	s_load_dwordx2 s[4:5], s[8:9], 0xf8
	v_readlane_b32 s10, v254, 41
	v_cndmask_b32_e32 v4, v210, v4, vcc
	v_lshlrev_b32_e32 v25, 2, v4
	v_xor_b32_e32 v4, 16, v210
	v_cmp_lt_i32_e32 vcc, v4, v3
	v_readlane_b32 s11, v254, 42
	s_lshl_b64 s[10:11], s[10:11], 2
	v_cndmask_b32_e32 v4, v210, v4, vcc
	v_lshlrev_b32_e32 v26, 2, v4
	v_xor_b32_e32 v4, 8, v210
	v_cmp_lt_i32_e32 vcc, v4, v3
	v_and_b32_e32 v20, 63, v2
	s_waitcnt lgkmcnt(0)
	s_add_u32 s4, s4, s10
	v_cndmask_b32_e32 v4, v210, v4, vcc
	v_lshlrev_b32_e32 v27, 2, v4
	v_xor_b32_e32 v4, 4, v210
	v_cmp_lt_i32_e32 vcc, v4, v3
	s_addc_u32 s5, s5, s11
	v_mov_b32_e32 v5, v1
	v_cndmask_b32_e32 v4, v210, v4, vcc
	v_lshlrev_b32_e32 v28, 2, v4
	v_xor_b32_e32 v4, 2, v210
	v_cmp_lt_i32_e32 vcc, v4, v3
	v_lshlrev_b32_e32 v18, 1, v20
	v_add_u32_e32 v12, s3, v24
	v_cndmask_b32_e32 v4, v210, v4, vcc
	v_lshlrev_b32_e32 v29, 2, v4
	v_xor_b32_e32 v4, 1, v210
	v_cmp_lt_i32_e32 vcc, v4, v3
	v_ashrrev_i32_e32 v13, 31, v12
	s_load_dwordx2 s[12:13], s[8:9], 0x108
	s_load_dwordx2 s[48:49], s[8:9], 0x138
	v_cndmask_b32_e32 v3, v210, v4, vcc
	v_lshlrev_b32_e32 v30, 2, v3
	v_lshlrev_b32_e32 v4, 4, v20
	v_and_b32_e32 v3, 15, v2
	v_lshl_add_u64 v[4:5], s[4:5], 0, v[4:5]
	v_readlane_b32 s4, v254, 43
	v_cvt_f32_ubyte0_e32 v3, v3
	v_mul_f32_e32 v8, 0xbf549a78, v3
	v_or_b32_e32 v6, s4, v18
	s_mov_b32 s4, 0xc2fc0000
	v_cmp_gt_f32_e32 vcc, s4, v8
	v_and_b32_e32 v2, 16, v2
	v_readlane_b32 s4, v254, 57
	v_cndmask_b32_e32 v8, 0, v209, vcc
	v_fmac_f32_e32 v8, 0xbf549a78, v3
	v_exp_f32_e32 v3, v8
	v_cndmask_b32_e32 v8, 0, v208, vcc
	v_cmp_eq_u32_e64 s[40:41], 0, v2
	v_readlane_b32 s5, v254, 58
	v_ldexp_f32 v31, v3, v8
	v_lshlrev_b64 v[2:3], 7, v[12:13]
	v_mov_b32_e32 v19, v1
	v_lshl_add_u64 v[2:3], s[4:5], 0, v[2:3]
	v_readlane_b32 s4, v254, 62
	v_lshl_add_u64 v[2:3], v[2:3], 0, v[18:19]
	v_lshlrev_b64 v[10:11], 9, v[12:13]
	v_readlane_b32 s5, v254, 63
	v_lshlrev_b32_e32 v19, 3, v20
	v_lshlrev_b32_e32 v32, 6, v12
	v_lshlrev_b32_e32 v33, 7, v12
	v_lshl_add_u64 v[8:9], s[4:5], 0, v[10:11]
	v_or_b32_e32 v10, v10, v19
	s_mov_b64 s[4:5], 0x10a18000
	v_lshlrev_b64 v[12:13], 12, v[12:13]
	v_lshlrev_b32_e32 v0, 2, v20
	v_lshl_add_u64 v[10:11], v[10:11], 0, s[4:5]
	v_or_b32_e32 v14, v12, v18
	v_mov_b32_e32 v15, v13
	s_mov_b64 s[4:5], 0x2448f00
	v_mov_b32_e32 v7, v1
	s_waitcnt lgkmcnt(0)
	s_add_u32 s50, s48, 0x3000000
	v_lshl_add_u64 v[14:15], v[14:15], 0, s[4:5]
	v_or_b32_e32 v16, v12, v0
	v_mov_b32_e32 v17, v13
	s_mov_b64 s[4:5], 0x2448e00
	v_lshl_add_u64 v[6:7], v[6:7], 2, s[12:13]
	s_addc_u32 s51, s49, 0
	v_cmp_gt_u32_e64 s[42:43], 32, v20
	v_lshl_add_u64 v[8:9], v[8:9], 0, v[0:1]
	v_lshl_add_u64 v[16:17], v[16:17], 0, s[4:5]
	v_or_b32_e32 v12, v12, v19
	s_mov_b64 s[52:53], 0
	v_lshlrev_b32_e32 v18, 2, v18
	v_lshlrev_b32_e32 v20, 2, v20
	global_load_dwordx4 v[100:103], v[4:5], off
	global_load_dwordx2 v[104:105], v[6:7], off
	v_lshl_add_u64 v[114:115], s[80:81], 0, v[12:13]
	s_nop 0
	v_add_co_u32_e32 v114, vcc, 0x2448000, v114
	s_nop 1
	v_addc_co_u32_e32 v115, vcc, 0, v115, vcc
	s_nop 1
	global_load_dwordx2 v[106:107], v[114:115], off offset:3072
	v_lshl_add_u64 v[116:117], v[114:115], 0, s[18:19]
	s_nop 1
	global_load_dwordx2 v[110:111], v[116:117], off offset:3072
	v_lshl_add_u64 v[114:115], s[80:81], 0, v[16:17]
	s_nop 1
	global_load_dword v108, v[114:115], off
	v_lshl_add_u64 v[116:117], v[114:115], 0, s[18:19]
	s_nop 1
	global_load_dword v112, v[116:117], off
	v_lshl_add_u64 v[114:115], s[80:81], 0, v[14:15]
	s_nop 1
	global_load_ushort v109, v[114:115], off
	v_lshl_add_u64 v[116:117], v[114:115], 0, s[18:19]
	s_nop 1
	global_load_ushort v113, v[116:117], off
	s_waitcnt vmcnt(0)
	s_branch .LBB0_556
.LBB0_555:
	s_or_b64 exec, exec, s[14:15]
	v_mov_b64_e32 v[106:107], v[110:111]
	v_mov_b32_e32 v108, v112
	v_mov_b32_e32 v109, v113
	v_bfe_u32 v19, v0, 16, 1
	v_add3_u32 v0, v0, v19, s27
	v_lshl_add_u64 v[22:23], s[80:81], 0, v[2:3]
	global_store_short_d16_hi v[22:23], v0, off
	v_add_u32_e32 v0, 8, v24
	v_cmp_lt_i32_e32 vcc, 7, v24
	v_add_u32_e32 v32, 0x200, v32
	v_add_u32_e32 v33, 0x400, v33
	v_lshl_add_u64 v[2:3], v[2:3], 0, s[94:95]
	v_lshl_add_u64 v[8:9], v[8:9], 0, s[16:17]
	v_lshl_add_u64 v[10:11], v[10:11], 0, s[16:17]
	v_lshl_add_u64 v[14:15], v[14:15], 0, s[18:19]
	v_lshl_add_u64 v[16:17], v[16:17], 0, s[18:19]
	v_lshl_add_u64 v[12:13], v[12:13], 0, s[18:19]
	s_or_b64 s[52:53], vcc, s[52:53]
	v_mov_b32_e32 v24, v0
	s_andn2_b64 exec, exec, s[52:53]
	s_cbranch_execz .LBB0_540
.LBB0_556:
	v_lshl_add_u64 v[22:23], s[80:81], 0, v[12:13]
	v_add_co_u32_e32 v22, vcc, 0x2448000, v22
	v_mov_b64_e32 v[34:35], v[100:101]
	v_mov_b64_e32 v[36:37], v[102:103]
	s_nop 0
	v_addc_co_u32_e32 v23, vcc, 0, v23, vcc
	v_mov_b64_e32 v[22:23], v[106:107]
	v_add_u32_e32 v21, s3, v24
	v_cmp_gt_i32_e64 s[44:45], s37, v21
	v_and_b32_e32 v39, 0xffff0000, v23
	v_lshlrev_b32_e32 v38, 16, v23
	v_and_b32_e32 v23, 0xffff0000, v22
	v_lshlrev_b32_e32 v22, 16, v22
	v_pk_mul_f32 v[42:43], v[22:23], v[22:23]
	v_pk_mul_f32 v[40:41], v[38:39], v[38:39]
	v_add_f32_e32 v0, v42, v43
	v_add_f32_e32 v0, v0, v40
	v_add_f32_e32 v0, v0, v41
	s_waitcnt lgkmcnt(0)
	s_nop 1
	v_add_f32_dpp v19, v0, v0 quad_perm:[1,0,3,2] row_mask:0xf bank_mask:0xf
	s_nop 1
	v_add_f32_dpp v19, v19, v19 quad_perm:[2,3,0,1] row_mask:0xf bank_mask:0xf
	s_nop 1
	v_add_f32_dpp v19, v19, v19 row_ror:4 row_mask:0xf bank_mask:0xf
	s_nop 1
	v_add_f32_dpp v19, v19, v19 row_ror:8 row_mask:0xf bank_mask:0xf
	s_nop 1
	v_readlane_b32 s96, v19, 0
	v_readlane_b32 s97, v19, 16
	v_readlane_b32 s98, v19, 32
	v_readlane_b32 s99, v19, 48
	v_mov_b32_e32 v0, s96
	v_add_f32_e32 v0, s97, v0
	v_add_f32_e32 v0, s98, v0
	v_add_f32_e32 v0, s99, v0
	v_fmamk_f32 v0, v0, 0x3b800000, v203
	v_cmp_gt_f32_e32 vcc, s87, v0
	v_mul_f32_e32 v19, 0x4b800000, v0
	s_nop 0
	v_cndmask_b32_e32 v0, v0, v19, vcc
	v_rsq_f32_e32 v0, v0
	s_nop 0
	v_mul_f32_e32 v19, 0x45800000, v0
	v_cndmask_b32_e32 v0, v0, v19, vcc
	v_pk_mul_f32 v[22:23], v[0:1], v[22:23] op_sel_hi:[0,1]
	v_pk_mul_f32 v[22:23], v[34:35], v[22:23]
	v_pk_mul_f32 v[34:35], v[0:1], v[38:39] op_sel_hi:[0,1]
	v_pk_mul_f32 v[34:35], v[36:37], v[34:35]
	v_cvt_pk_bf16_f32 v22, v22, v23
	v_cvt_pk_bf16_f32 v23, v34, v35
	v_lshl_add_u64 v[34:35], s[80:81], 0, v[10:11]
	global_store_dwordx2 v[34:35], v[22:23], off
	v_lshl_add_u64 v[22:23], s[80:81], 0, v[16:17]
	v_mov_b32_e32 v0, v108
	v_and_b32_e32 v23, 0xffff0000, v0
	v_lshlrev_b32_e32 v22, 16, v0
	v_pk_mul_f32 v[34:35], v[22:23], v[22:23]
	s_nop 0
	v_add_f32_e32 v0, v34, v35
	v_mov_b64_e32 v[34:35], v[104:105]
	s_waitcnt lgkmcnt(0)
	s_nop 1
	v_add_f32_dpp v19, v0, v0 quad_perm:[1,0,3,2] row_mask:0xf bank_mask:0xf
	s_nop 1
	v_add_f32_dpp v19, v19, v19 quad_perm:[2,3,0,1] row_mask:0xf bank_mask:0xf
	s_nop 1
	v_add_f32_dpp v19, v19, v19 row_ror:4 row_mask:0xf bank_mask:0xf
	s_nop 1
	v_add_f32_dpp v19, v19, v19 row_ror:8 row_mask:0xf bank_mask:0xf
	s_nop 1
	v_readlane_b32 s96, v19, 0
	v_readlane_b32 s97, v19, 16
	v_readlane_b32 s98, v19, 32
	v_readlane_b32 s99, v19, 48
	v_mov_b32_e32 v0, s96
	v_add_f32_e32 v0, s97, v0
	v_add_f32_e32 v0, s98, v0
	v_add_f32_e32 v0, s99, v0
	v_fmamk_f32 v0, v0, 0x3c000000, v203
	v_cmp_gt_f32_e32 vcc, s87, v0
	v_mul_f32_e32 v19, 0x4b800000, v0
	s_nop 0
	v_cndmask_b32_e32 v0, v0, v19, vcc
	v_rsq_f32_e32 v0, v0
	s_nop 0
	v_mul_f32_e32 v19, 0x45800000, v0
	v_cndmask_b32_e32 v0, v0, v19, vcc
	v_pk_mul_f32 v[22:23], v[0:1], v[22:23] op_sel_hi:[0,1]
	v_cmp_lt_i32_e32 vcc, s91, v21
	v_pk_mul_f32 v[22:23], v[34:35], v[22:23]
	s_nop 0
	v_cvt_pk_bf16_f32 v0, v22, v23
	v_lshl_add_u64 v[34:35], s[80:81], 0, v[8:9]
	global_store_dword v[34:35], v0, off
	v_ashrrev_i32_e32 v0, 7, v21
	v_and_b32_e32 v34, -2, v0
	s_and_saveexec_b64 s[14:15], s[44:45]
	s_cbranch_execz .LBB0_558
	v_add_u32_e32 v36, s58, v34
	v_ashrrev_i32_e32 v37, 31, v36
	v_and_b32_e32 v0, 0x7f80, v33
	v_lshlrev_b64 v[36:37], 17, v[36:37]
	v_lshl_add_u64 v[36:37], s[50:51], 0, v[36:37]
	v_lshlrev_b32_e32 v0, 2, v0
	v_lshl_add_u64 v[36:37], v[36:37], 0, v[0:1]
	v_mov_b32_e32 v19, v1
	v_lshl_add_u64 v[36:37], v[36:37], 0, v[18:19]
	global_store_dwordx2 v[36:37], v[22:23], off
.LBB0_558:
	s_or_b64 exec, exec, s[14:15]
	v_lshl_add_u64 v[22:23], s[80:81], 0, v[14:15]
	v_mov_b32_e32 v0, v109
	v_lshlrev_b32_e32 v19, 16, v0
	s_and_saveexec_b64 s[4:5], vcc
	s_xor_b64 s[14:15], exec, s[4:5]
	s_cbranch_execz .LBB0_560
	v_bfe_u32 v22, v21, 6, 4
	v_and_b32_e32 v21, 63, v21
	v_cndmask_b32_e64 v21, v21, v22, s[40:41]
	v_cvt_f32_ubyte0_e32 v21, v21
	v_mul_f32_e32 v21, v31, v21
	ds_bpermute_b32 v0, v25, v19
	v_mul_f32_e32 v21, 0.15915494, v21
	v_sin_f32_e32 v22, v21
	v_cos_f32_e32 v21, v21
	s_waitcnt lgkmcnt(0)
	v_mul_f32_e32 v0, v22, v0
	v_cndmask_b32_e64 v0, v0, -v0, s[42:43]
	v_fmac_f32_e32 v0, v21, v19
